# added: grid-barrier followers poll the top-level generation word directly (one hop fewer); keeps cvt_pk packs, counted vmcnt in EpiBranch, early FoX K/V DMA issue
# baseline (speedup 1.0000x reference)
; __device__ __forceinline__ unsigned xb_ld(unsigned* p)              { return __hip_atomic_load(p, __ATOMIC_RELAXED, __HIP_MEMORY_SCOPE_AGENT); }
; __device__ __forceinline__ unsigned xb_add(unsigned* p, unsigned v) { return __hip_atomic_fetch_add(p, v, __ATOMIC_RELAXED, __HIP_MEMORY_SCOPE_AGENT); }
; #define XB_SPIN(cond, bar) do { unsigned _sp = 0; while (cond) { __builtin_amdgcn_s_sleep(1); \
;     if ((++_sp & 255u) == 0u) { if (xb_ld(&(bar)[XB_TMO])) break; if (_sp > XB_SPIN_CAP) { atomicAdd(&(bar)[XB_TMO], 1u); break; } } } } while (0)
; __device__ __forceinline__ void xcd_barrier(const XcdBarrier& b) {
;     ...
;         const unsigned old = xb_add(&bar[XB_XSUB(b.x)], 1u);
;         const unsigned gen = old / nloc;
;         if (old + 1u == (gen + 1u) * nloc) {
;             __builtin_amdgcn_fence(__ATOMIC_RELEASE, "agent");
;             asm volatile("s_waitcnt vmcnt(0)" ::: "memory");
;             const unsigned og = xb_add(&bar[XB_TOP], 1u);
;             const unsigned tg = og / nx;
;             if (og + 1u == (tg + 1u) * nx) xb_add(&bar[XB_TOPGEN], 1u);
;             else XB_SPIN(xb_ld(&bar[XB_TOPGEN]) == tg, bar);
;             __builtin_amdgcn_fence(__ATOMIC_ACQUIRE, "agent");
;             xb_add(&bar[XB_XGEN(b.x)], 1u);
;             asm volatile("s_waitcnt vmcnt(0)" ::: "memory");
;         } else {
;             XB_SPIN(xb_ld(&bar[XB_XGEN(b.x)]) == gen, bar);
;             __builtin_amdgcn_fence(__ATOMIC_ACQUIRE, "agent");
;             asm volatile("s_waitcnt vmcnt(0)" ::: "memory");
;         }
.LBB9_839:
	s_or_b64 exec, exec, s[8:9]
	v_cvt_f32_u32_e32 v5, v3
	s_waitcnt vmcnt(0)
	v_readfirstlane_b32 s6, v4
	v_sub_u32_e32 v4, 0, v3
	v_rcp_iflag_f32_e32 v5, v5
	v_add_u32_e32 v6, s6, v0
	v_mul_f32_e32 v5, 0x4f7ffffe, v5
	v_cvt_u32_f32_e32 v5, v5
	v_mul_lo_u32 v0, v4, v5
	v_mul_hi_u32 v0, v5, v0
	v_add_u32_e32 v0, v5, v0
	v_mul_hi_u32 v0, v6, v0
	v_mul_lo_u32 v4, v0, v3
	v_sub_u32_e32 v4, v6, v4
	v_add_u32_e32 v5, 1, v0
	v_cmp_ge_u32_e32 vcc, v4, v3
	s_nop 1
	v_cndmask_b32_e32 v0, v0, v5, vcc
	v_sub_u32_e32 v5, v4, v3
	v_cndmask_b32_e32 v4, v4, v5, vcc
	v_add_u32_e32 v5, 1, v0
	v_cmp_ge_u32_e32 vcc, v4, v3
	v_add_u32_e32 v4, 1, v6
	s_nop 0
	v_cndmask_b32_e32 v0, v0, v5, vcc
	v_mul_lo_u32 v5, v3, v0
	v_add_u32_e32 v3, v5, v3
	v_cmp_ne_u32_e32 vcc, v4, v3
	s_and_saveexec_b64 s[6:7], vcc
	s_xor_b64 s[6:7], exec, s[6:7]
	s_cbranch_execz .LBB9_857
	s_waitcnt lgkmcnt(0)
	v_mov_b32_e32 v2, 0x7500
	global_load_dword v2, v2, s[76:77] sc1
	s_add_u32 s12, s76, 0x7500
	s_addc_u32 s13, s77, 0
	s_waitcnt vmcnt(0)
	v_cmp_eq_u32_e32 vcc, v2, v0
	s_and_saveexec_b64 s[8:9], vcc
	s_cbranch_execz .LBB9_856
	s_add_u32 s10, s76, 0x4200
	s_addc_u32 s11, s77, 0
	s_mov_b32 s24, 1
	s_mov_b64 s[14:15], 0
	s_branch .LBB9_843
